# attention item epilogue: da_norm loads issued ahead instead of one load and full wait per output group
# speedup vs baseline: 1.0031x; 1.0031x over previous
; __device__ __forceinline__ float shx(float v, int mask, int lane) { return __int_as_float(__builtin_amdgcn_ds_bpermute((lane ^ mask) << 2, __float_as_int(v))); }
; __device__ __forceinline__ unsigned pack2(float lo, float hi) { unsigned r; asm("v_cvt_pk_bf16_f32 %0, %1, %2" : "=v"(r) : "v"(lo), "v"(hi)); return r; }
; __device__ __forceinline__ void attn_phase(int wv, PP P, int L, LAS unsigned char* lds) {
;     ...
;         const float* dn = P->da_norm + (size_t)L * 128;
;         const float i0 = __builtin_amdgcn_rcpf(lrun[0]), i1 = lam * __builtin_amdgcn_rcpf(lrun[1]); float ss = 0.f;
; #pragma unroll
;         for (int e = 0; e < 8; ++e) { O[0][e] = O[0][e] * i0 - O[1][e] * i1; ss += O[0][e][0] * O[0][e][0] + O[0][e][1] * O[0][e][1] + O[0][e][2] * O[0][e][2] + O[0][e][3] * O[0][e][3]; }
;         ss += shx(ss, 16, lane); ss += shx(ss, 32, lane);
;         const int pos = q0 + w * 16 + fr; const float r = (pos < PADN) ? 0.f : rsqrtf(ss * (1.0f / 128.0f) + EPS) * (1.0f - lam_init);
; #pragma unroll
;         for (int e = 0; e < 8; ++e) { const f32x4 g4 = *(const f32x4*)(dn + e * 16 + fq * 4); u32x2 o; o.x = pack2(O[0][e][0] * r * g4[0], O[0][e][1] * r * g4[1]); o.y = pack2(O[0][e][2] * r * g4[2], O[0][e][3] * r * g4[3]);
;             if (pos < PADN) { o.x = 0u; o.y = 0u; }
;             if (wact) *(u32x2*)(cat + ((size_t)b * LP + pos) * D + 1536 + h * 128 + e * 16 + fq * 4) = o; }
.LBB0_377:
	s_or_b64 exec, exec, s[26:27]
	s_add_u32 s24, s24, s20
	s_addc_u32 s25, s25, s21
	v_lshlrev_b32_e32 v36, 2, v128
	global_load_dwordx4 v[238:241], v36, s[24:25]
	global_load_dwordx4 v[242:245], v36, s[24:25] offset:64
	global_load_dwordx4 v[246:249], v36, s[24:25] offset:128
	global_load_dwordx4 v[250:253], v36, s[24:25] offset:192
	s_waitcnt lgkmcnt(0)
	v_lshl_add_u64 v[16:17], s[22:23], 0, v[132:133]
	v_lshlrev_b64 v[16:17], 12, v[16:17]
	v_lshl_add_u64 v[16:17], s[12:13], 0, v[16:17]
	s_mov_b32 s9, s57
	v_mul_f32_e32 v34, v34, v38
	v_mul_f32_e32 v35, v35, v38
	v_lshl_add_u64 v[16:17], v[16:17], 0, s[8:9]
	v_lshlrev_b32_e32 v2, 1, v128
	v_lshl_add_u64 v[16:17], v[16:17], 0, v[2:3]
	v_mul_f32_e32 v2, v48, v38
	v_mul_f32_e32 v37, v49, v38
	s_andn2_b64 vcc, exec, s[4:5]
	s_waitcnt vmcnt(3)
	v_mul_f32_e32 v34, v34, v240
	v_mul_f32_e32 v35, v35, v241
	v_cvt_pk_bf16_f32 v34, v34, v35
	v_cndmask_b32_e64 v35, 0, 1, s[4:5]
	v_mul_f32_e32 v2, v2, v238
	v_cmp_ne_u32_e64 s[8:9], 1, v35
	v_mul_f32_e32 v37, v37, v239
	v_cvt_pk_bf16_f32 v2, v2, v37
	s_cbranch_vccnz .LBB0_379
	v_cndmask_b32_e64 v35, v34, 0, s[6:7]
	v_cndmask_b32_e64 v34, v2, 0, s[6:7]
	global_store_dwordx2 v[16:17], v[34:35], off offset:3072
.LBB0_379:
	v_mov_b32_e32 v37, v3
	v_lshl_add_u64 v[34:35], s[24:25], 0, v[36:37]
	global_load_dwordx4 v[238:241], v36, s[24:25] offset:256
	v_mul_f32_e32 v2, v32, v38
	v_mul_f32_e32 v30, v30, v38
	v_mul_f32_e32 v32, v33, v38
	v_mul_f32_e32 v31, v31, v38
	s_and_b64 vcc, exec, s[8:9]
	s_waitcnt vmcnt(4)
	v_mul_f32_e32 v2, v2, v242
	v_mul_f32_e32 v30, v30, v244
	v_mul_f32_e32 v32, v32, v243
	v_mul_f32_e32 v31, v31, v245
	v_cvt_pk_bf16_f32 v2, v2, v32
	v_cvt_pk_bf16_f32 v30, v30, v31
	s_cbranch_vccnz .LBB0_381
	v_cndmask_b32_e64 v31, v30, 0, s[6:7]
	v_cndmask_b32_e64 v30, v2, 0, s[6:7]
	global_store_dwordx2 v[16:17], v[30:31], off offset:3104
.LBB0_381:
	global_load_dwordx4 v[242:245], v36, s[24:25] offset:320
	v_mul_f32_e32 v2, v28, v38
	v_mul_f32_e32 v26, v26, v38
	v_mul_f32_e32 v28, v29, v38
	v_mul_f32_e32 v27, v27, v38
	s_and_b64 vcc, exec, s[8:9]
	s_waitcnt vmcnt(5)
	v_mul_f32_e32 v2, v2, v246
	v_mul_f32_e32 v26, v26, v248
	v_mul_f32_e32 v28, v28, v247
	v_mul_f32_e32 v27, v27, v249
	v_cvt_pk_bf16_f32 v2, v2, v28
	v_cvt_pk_bf16_f32 v26, v26, v27
	s_cbranch_vccnz .LBB0_383
	v_cndmask_b32_e64 v27, v26, 0, s[6:7]
	v_cndmask_b32_e64 v26, v2, 0, s[6:7]
	global_store_dwordx2 v[16:17], v[26:27], off offset:3136
.LBB0_383:
	global_load_dwordx4 v[246:249], v36, s[24:25] offset:384
	v_mul_f32_e32 v2, v24, v38
	v_mul_f32_e32 v22, v22, v38
	v_mul_f32_e32 v24, v25, v38
	v_mul_f32_e32 v23, v23, v38
	s_and_b64 vcc, exec, s[8:9]
	s_waitcnt vmcnt(6)
	v_mul_f32_e32 v2, v2, v250
	v_mul_f32_e32 v22, v22, v252
	v_mul_f32_e32 v24, v24, v251
	v_mul_f32_e32 v23, v23, v253
	v_cvt_pk_bf16_f32 v2, v2, v24
	v_cvt_pk_bf16_f32 v22, v22, v23
	s_cbranch_vccnz .LBB0_385
	v_cndmask_b32_e64 v23, v22, 0, s[6:7]
	v_cndmask_b32_e64 v22, v2, 0, s[6:7]
	global_store_dwordx2 v[16:17], v[22:23], off offset:3168
.LBB0_385:
	global_load_dwordx4 v[250:253], v36, s[24:25] offset:448
	v_mul_f32_e32 v2, v20, v38
	v_mul_f32_e32 v18, v18, v38
	v_mul_f32_e32 v20, v21, v38
	v_mul_f32_e32 v19, v19, v38
	s_and_b64 vcc, exec, s[8:9]
	s_waitcnt vmcnt(6)
	v_mul_f32_e32 v2, v2, v238
	v_mul_f32_e32 v18, v18, v240
	v_mul_f32_e32 v20, v20, v239
	v_mul_f32_e32 v19, v19, v241
	v_cvt_pk_bf16_f32 v2, v2, v20
	v_cvt_pk_bf16_f32 v18, v18, v19
	s_cbranch_vccnz .LBB0_387
	v_cndmask_b32_e64 v19, v18, 0, s[6:7]
	v_cndmask_b32_e64 v18, v2, 0, s[6:7]
	global_store_dwordx2 v[16:17], v[18:19], off offset:3200
.LBB0_387:
	v_mul_f32_e32 v2, v14, v38
	v_mul_f32_e32 v12, v12, v38
	v_mul_f32_e32 v14, v15, v38
	v_mul_f32_e32 v13, v13, v38
	s_and_b64 vcc, exec, s[8:9]
	s_waitcnt vmcnt(5)
	v_mul_f32_e32 v2, v2, v242
	v_mul_f32_e32 v12, v12, v244
	v_mul_f32_e32 v14, v14, v243
	v_mul_f32_e32 v13, v13, v245
	v_cvt_pk_bf16_f32 v2, v2, v14
	v_cvt_pk_bf16_f32 v12, v12, v13
	s_cbranch_vccnz .LBB0_389
	v_cndmask_b32_e64 v13, v12, 0, s[6:7]
	v_cndmask_b32_e64 v12, v2, 0, s[6:7]
	global_store_dwordx2 v[16:17], v[12:13], off offset:3232
.LBB0_389:
	v_mul_f32_e32 v2, v10, v38
	v_mul_f32_e32 v8, v8, v38
	v_mul_f32_e32 v10, v11, v38
	v_mul_f32_e32 v9, v9, v38
	s_and_b64 vcc, exec, s[8:9]
	s_waitcnt vmcnt(4)
	v_mul_f32_e32 v2, v2, v246
	v_mul_f32_e32 v8, v8, v248
	v_mul_f32_e32 v10, v10, v247
	v_mul_f32_e32 v9, v9, v249
	v_cvt_pk_bf16_f32 v2, v2, v10
	v_cvt_pk_bf16_f32 v8, v8, v9
	s_cbranch_vccnz .LBB0_391
	v_cndmask_b32_e64 v9, v8, 0, s[6:7]
	v_cndmask_b32_e64 v8, v2, 0, s[6:7]
	global_store_dwordx2 v[16:17], v[8:9], off offset:3264
.LBB0_391:
	v_mul_f32_e32 v2, v6, v38
	v_mul_f32_e32 v4, v4, v38
	v_mul_f32_e32 v6, v7, v38
	v_mul_f32_e32 v5, v5, v38
	s_and_b64 vcc, exec, s[8:9]
	s_waitcnt vmcnt(3)
	v_mul_f32_e32 v2, v2, v250
	v_mul_f32_e32 v4, v4, v252
	v_mul_f32_e32 v6, v6, v251
	v_mul_f32_e32 v5, v5, v253
	v_cvt_pk_bf16_f32 v2, v2, v6
	v_cvt_pk_bf16_f32 v4, v4, v5
	s_cbranch_vccnz .LBB0_354
	v_cndmask_b32_e64 v5, v4, 0, s[6:7]
	v_cndmask_b32_e64 v4, v2, 0, s[6:7]
	global_store_dwordx2 v[16:17], v[4:5], off offset:3296
	s_branch .LBB0_354
